# v27 + x-RMSNorm (phase 0) and grouped RMSNorm (phase 16) row loops: next row prefetched, gain loads hoisted out of the loop
# baseline (speedup 1.0000x reference)
; __device__ __forceinline__ unsigned cvt_pk_bf16(float lo, float hi) { unsigned r; asm volatile("v_cvt_pk_bf16_f32 %0, %1, %2" : "=v"(r) : "v"(lo), "v"(hi)); return r; }
; __device__ __forceinline__ float bflo(unsigned w) { return __uint_as_float(w << 16); }
; __device__ __forceinline__ float bfhi(unsigned w) { return __uint_as_float(w & 0xffff0000u); }
; __device__ __forceinline__ void gnorm_phase(bf16_t* YS, const float* ng, int gw, int NGW, int lane) {
;     for (int row = gw; row < T; row += NGW) {
;         bf16_t* p = YS + (size_t)row * SSD_INNER + lane * 8; u32x4 v[8]; float sq[8];
; #pragma unroll
;         for (int g = 0; g < 8; ++g) v[g] = *(const u32x4*)(p + g * 512);
; #pragma unroll
;         for (int g = 0; g < 8; ++g) { const float f0 = bflo(v[g].x), f1 = bfhi(v[g].x), f2 = bflo(v[g].y), f3 = bfhi(v[g].y), f4 = bflo(v[g].z), f5 = bfhi(v[g].z), f6 = bflo(v[g].w), f7 = bfhi(v[g].w);
;             sq[g] = ((f0 * f0 + f1 * f1) + (f2 * f2 + f3 * f3)) + ((f4 * f4 + f5 * f5) + (f6 * f6 + f7 * f7)); }
; #pragma unroll
;         for (int o = 1; o < 64; o <<= 1)
; #pragma unroll
;             for (int g = 0; g < 8; ++g) sq[g] += __shfl_xor(sq[g], o);
; #pragma unroll
;         for (int g = 0; g < 8; ++g) { const float rstd = rsqrtf(sq[g] * (1.f / 512.f) + EPS);
;             const f32x4 g0 = *(const f32x4*)(ng + g * 512 + lane * 8), g1 = *(const f32x4*)(ng + g * 512 + lane * 8 + 4);
;             u32x4 o; o.x = cvt_pk_bf16(bflo(v[g].x) * rstd * g0[0], bfhi(v[g].x) * rstd * g0[1]); o.y = cvt_pk_bf16(bflo(v[g].y) * rstd * g0[2], bfhi(v[g].y) * rstd * g0[3]);
;             o.z = cvt_pk_bf16(bflo(v[g].z) * rstd * g1[0], bfhi(v[g].z) * rstd * g1[1]); o.w = cvt_pk_bf16(bflo(v[g].w) * rstd * g1[2], bfhi(v[g].w) * rstd * g1[3]);
;             *(u32x4*)(p + g * 512) = o; }
.LBB0_82:
	s_and_b64 vcc, exec, s[2:3]
	s_cbranch_vccz .LBB0_189
	s_cmp_gt_i32 s76, 13
	s_mov_b64 s[2:3], -1
	s_cbranch_scc0 .LBB0_158
	s_cmp_lt_i32 s76, 15
	s_cbranch_scc1 .LBB0_148
	s_cmp_gt_i32 s76, 15
	s_cbranch_scc0 .LBB0_90
	v_readlane_b32 s2, v254, 39
	s_cmpk_gt_i32 s2, 0x1fff
	s_mov_b32 s10, 0x3b000000
	s_mov_b32 s12, 0x358637bd
	v_readlane_b32 s14, v254, 41
	v_readlane_b32 s3, v254, 40
	v_readlane_b32 s15, v254, 42
	s_cbranch_scc1 .LBB0_89
	s_load_dwordx2 s[2:3], s[92:93], 0xa8
	s_load_dwordx2 s[6:7], s[92:93], 0xe8
	v_lshlrev_b32_e32 v2, 5, v211
	s_waitcnt lgkmcnt(0)
	v_mov_b32_e32 v3, v0
	v_xor_b32_e32 v1, 1, v200
	v_lshl_add_u64 v[26:27], s[2:3], 0, v[2:3]
	s_mov_b64 s[2:3], 0x1000
	v_cmp_lt_i32_e32 vcc, v1, v202
	v_xor_b32_e32 v2, 2, v200
	v_lshl_add_u64 v[28:29], v[26:27], 0, s[2:3]
	s_mov_b64 s[2:3], 0x1800
	v_cndmask_b32_e32 v1, v200, v1, vcc
	v_cmp_lt_i32_e32 vcc, v2, v202
	v_lshl_add_u64 v[30:31], v[26:27], 0, s[2:3]
	s_mov_b64 s[2:3], 0x2000
	v_cndmask_b32_e32 v2, v200, v2, vcc
	v_lshl_add_u64 v[32:33], v[26:27], 0, s[2:3]
	s_mov_b64 s[2:3], 0x2800
	v_lshlrev_b32_e32 v86, 2, v2
	v_xor_b32_e32 v2, 4, v200
	v_lshl_add_u64 v[34:35], v[26:27], 0, s[2:3]
	s_mov_b64 s[2:3], 0x3000
	v_cmp_lt_i32_e32 vcc, v2, v202
	v_lshl_add_u64 v[36:37], v[26:27], 0, s[2:3]
	s_mov_b64 s[2:3], 0x3800
	v_cndmask_b32_e32 v2, v200, v2, vcc
	v_cmp_lt_i32_e32 vcc, v206, v202
	v_lshl_add_u64 v[38:39], v[26:27], 0, s[2:3]
	v_readlane_b32 s2, v254, 39
	v_lshlrev_b32_e32 v87, 2, v2
	v_cndmask_b32_e32 v2, v200, v206, vcc
	v_cmp_lt_i32_e32 vcc, v207, v202
	v_readlane_b32 s3, v254, 40
	s_mov_b32 s8, s2
	s_ashr_i32 s9, s2, 31
	v_lshlrev_b32_e32 v88, 2, v2
	v_cndmask_b32_e32 v2, v200, v207, vcc
	v_cmp_lt_i32_e32 vcc, v208, v202
	s_lshl_b64 s[2:3], s[8:9], 13
	v_lshlrev_b32_e32 v89, 2, v2
	v_cndmask_b32_e32 v2, v200, v208, vcc
	s_add_u32 s2, s6, s2
	v_lshlrev_b32_e32 v90, 2, v2
	v_lshlrev_b32_e32 v2, 4, v211
	s_addc_u32 s3, s7, s3
	s_mov_b32 s6, s8
	v_lshl_add_u64 v[2:3], s[2:3], 0, v[2:3]
	s_mov_b64 s[2:3], 0x14c00000
	s_ashr_i32 s15, s14, 31
	v_writelane_b32 v254, s6, 39
	v_lshlrev_b32_e32 v1, 2, v1
	v_lshl_add_u64 v[40:41], v[2:3], 0, s[2:3]
	s_lshl_b64 s[2:3], s[14:15], 13
	v_writelane_b32 v254, s7, 40
	global_load_dwordx4 v[116:119], v[40:41], off
	global_load_dwordx4 v[120:123], v[40:41], off offset:1024
	global_load_dwordx4 v[124:127], v[40:41], off offset:2048
	global_load_dwordx4 v[128:131], v[40:41], off offset:3072
	v_add_co_u32_e32 v140, vcc, 0x1000, v40
	s_nop 1
	v_addc_co_u32_e32 v141, vcc, 0, v41, vcc
	global_load_dwordx4 v[132:135], v[140:141], off
	global_load_dwordx4 v[136:139], v[140:141], off offset:1024
	global_load_dwordx4 v[148:151], v[140:141], off offset:2048
	global_load_dwordx4 v[156:159], v[140:141], off offset:3072
	global_load_dwordx4 v[160:163], v[26:27], off offset:16
	global_load_dwordx4 v[164:167], v[26:27], off
	global_load_dwordx4 v[168:171], v[26:27], off offset:2048
	global_load_dwordx4 v[172:175], v[26:27], off offset:2064
	global_load_dwordx4 v[176:179], v[28:29], off
	global_load_dwordx4 v[180:183], v[28:29], off offset:16
	global_load_dwordx4 v[184:187], v[30:31], off
	global_load_dwordx4 v[188:191], v[30:31], off offset:16
	global_load_dwordx4 v[192:195], v[32:33], off
	global_load_dwordx4 v[214:217], v[32:33], off offset:16
	global_load_dwordx4 v[218:221], v[34:35], off
	global_load_dwordx4 v[222:225], v[34:35], off offset:16
	global_load_dwordx4 v[226:229], v[36:37], off
	global_load_dwordx4 v[230:233], v[36:37], off offset:16
	global_load_dwordx4 v[234:237], v[38:39], off
	global_load_dwordx4 v[238:241], v[38:39], off offset:16
	s_waitcnt vmcnt(0)
.LBB0_88:
	v_add_co_u32_e32 v42, vcc, 0x1000, v40
	s_nop 1
	v_addc_co_u32_e32 v43, vcc, 0, v41, vcc
	v_mov_b64_e32 v[44:45], s[12:13]
	s_add_i32 s8, s8, s14
	s_cmpk_gt_i32 s8, 0x1fff
	s_waitcnt vmcnt(8)
	v_mov_b64_e32 v[46:47], v[116:117]
	v_mov_b64_e32 v[48:49], v[118:119]
	v_mov_b64_e32 v[50:51], v[120:121]
	v_mov_b64_e32 v[52:53], v[122:123]
	v_mov_b64_e32 v[22:23], v[124:125]
	v_mov_b64_e32 v[24:25], v[126:127]
	v_mov_b64_e32 v[18:19], v[128:129]
	v_mov_b64_e32 v[20:21], v[130:131]
	v_mov_b64_e32 v[92:93], v[132:133]
	v_mov_b64_e32 v[94:95], v[134:135]
	v_mov_b64_e32 v[96:97], v[136:137]
	v_mov_b64_e32 v[98:99], v[138:139]
	v_mov_b64_e32 v[6:7], v[148:149]
	v_mov_b64_e32 v[8:9], v[150:151]
	v_mov_b64_e32 v[2:3], v[156:157]
	v_mov_b64_e32 v[4:5], v[158:159]
	v_mov_b64_e32 v[10:11], v[160:161]
	v_mov_b64_e32 v[12:13], v[162:163]
	v_mov_b64_e32 v[14:15], v[164:165]
	v_mov_b64_e32 v[16:17], v[166:167]
	s_cbranch_scc1 .Lgn_noprefetch
	v_lshl_add_u64 v[140:141], v[40:41], 0, s[2:3]
	global_load_dwordx4 v[116:119], v[140:141], off
	global_load_dwordx4 v[120:123], v[140:141], off offset:1024
	global_load_dwordx4 v[124:127], v[140:141], off offset:2048
	global_load_dwordx4 v[128:131], v[140:141], off offset:3072
	v_lshl_add_u64 v[140:141], v[42:43], 0, s[2:3]
	global_load_dwordx4 v[132:135], v[140:141], off
	global_load_dwordx4 v[136:139], v[140:141], off offset:1024
	global_load_dwordx4 v[148:151], v[140:141], off offset:2048
	global_load_dwordx4 v[156:159], v[140:141], off offset:3072
; __device__ __forceinline__ float bflo(unsigned w) { return __uint_as_float(w << 16); }
; __device__ __forceinline__ float bfhi(unsigned w) { return __uint_as_float(w & 0xffff0000u); }
; __device__ __forceinline__ void gnorm_phase(bf16_t* YS, const float* ng, int gw, int NGW, int lane) {
;     ...
;         for (int g = 0; g < 8; ++g) v[g] = *(const u32x4*)(p + g * 512);
; #pragma unroll
;         for (int g = 0; g < 8; ++g) { const float f0 = bflo(v[g].x), f1 = bfhi(v[g].x), f2 = bflo(v[g].y), f3 = bfhi(v[g].y), f4 = bflo(v[g].z), f5 = bfhi(v[g].z), f6 = bflo(v[g].w), f7 = bfhi(v[g].w);
;             sq[g] = ((f0 * f0 + f1 * f1) + (f2 * f2 + f3 * f3)) + ((f4 * f4 + f5 * f5) + (f6 * f6 + f7 * f7)); }
; #pragma unroll
;         for (int o = 1; o < 64; o <<= 1)
; #pragma unroll
;             for (int g = 0; g < 8; ++g) sq[g] += __shfl_xor(sq[g], o);
.Lgn_noprefetch:
	v_and_b32_e32 v81, 0xffff0000, v48
	v_and_b32_e32 v80, 0xffff0000, v46
	v_and_b32_e32 v85, 0xffff0000, v49
	v_and_b32_e32 v84, 0xffff0000, v47
	v_and_b32_e32 v73, 0xffff0000, v52
	v_and_b32_e32 v72, 0xffff0000, v50
	v_and_b32_e32 v77, 0xffff0000, v53
	v_and_b32_e32 v76, 0xffff0000, v51
	v_lshlrev_b32_e32 v79, 16, v48
	v_lshlrev_b32_e32 v78, 16, v46
	v_lshlrev_b32_e32 v83, 16, v49
	v_lshlrev_b32_e32 v82, 16, v47
	v_lshlrev_b32_e32 v71, 16, v52
	v_lshlrev_b32_e32 v70, 16, v50
	v_lshlrev_b32_e32 v75, 16, v53
	v_lshlrev_b32_e32 v74, 16, v51
	v_lshlrev_b32_e32 v63, 16, v24
	v_lshlrev_b32_e32 v62, 16, v22
	v_and_b32_e32 v65, 0xffff0000, v24
	v_and_b32_e32 v64, 0xffff0000, v22
	v_lshlrev_b32_e32 v67, 16, v25
	v_lshlrev_b32_e32 v66, 16, v23
	v_and_b32_e32 v69, 0xffff0000, v25
	v_and_b32_e32 v68, 0xffff0000, v23
	v_lshlrev_b32_e32 v55, 16, v20
	v_lshlrev_b32_e32 v54, 16, v18
	v_and_b32_e32 v57, 0xffff0000, v20
	v_and_b32_e32 v56, 0xffff0000, v18
	v_lshlrev_b32_e32 v59, 16, v21
	v_lshlrev_b32_e32 v58, 16, v19
	v_and_b32_e32 v61, 0xffff0000, v21
	v_and_b32_e32 v60, 0xffff0000, v19
	v_pk_mul_f32 v[18:19], v[80:81], v[80:81]
	v_pk_mul_f32 v[20:21], v[84:85], v[84:85]
	v_pk_mul_f32 v[22:23], v[72:73], v[72:73]
	v_pk_mul_f32 v[24:25], v[76:77], v[76:77]
	v_pk_mul_f32 v[46:47], v[64:65], v[64:65]
	v_pk_mul_f32 v[48:49], v[68:69], v[68:69]
	v_pk_mul_f32 v[50:51], v[56:57], v[56:57]
	v_pk_mul_f32 v[52:53], v[60:61], v[60:61]
	v_pk_fma_f32 v[100:101], v[78:79], v[78:79], v[18:19]
	v_pk_fma_f32 v[102:103], v[82:83], v[82:83], v[20:21]
	v_pk_fma_f32 v[104:105], v[70:71], v[70:71], v[22:23]
	v_pk_fma_f32 v[106:107], v[74:75], v[74:75], v[24:25]
	v_pk_fma_f32 v[108:109], v[62:63], v[62:63], v[46:47]
	v_pk_fma_f32 v[110:111], v[66:67], v[66:67], v[48:49]
	v_pk_fma_f32 v[112:113], v[54:55], v[54:55], v[50:51]
	v_pk_fma_f32 v[114:115], v[58:59], v[58:59], v[52:53]
	v_lshlrev_b32_e32 v53, 16, v94
	v_lshlrev_b32_e32 v52, 16, v92
	v_and_b32_e32 v51, 0xffff0000, v94
	v_and_b32_e32 v50, 0xffff0000, v92
	v_lshlrev_b32_e32 v49, 16, v95
	v_lshlrev_b32_e32 v48, 16, v93
	v_and_b32_e32 v47, 0xffff0000, v95
	v_and_b32_e32 v46, 0xffff0000, v93
	v_pk_add_f32 v[92:93], v[100:101], v[102:103]
	v_pk_add_f32 v[94:95], v[104:105], v[106:107]
	v_lshlrev_b32_e32 v19, 16, v98
	v_lshlrev_b32_e32 v18, 16, v96
	v_and_b32_e32 v21, 0xffff0000, v98
	v_and_b32_e32 v20, 0xffff0000, v96
	v_lshlrev_b32_e32 v23, 16, v99
	v_lshlrev_b32_e32 v22, 16, v97
	v_and_b32_e32 v25, 0xffff0000, v99
	v_and_b32_e32 v24, 0xffff0000, v97
	v_pk_add_f32 v[96:97], v[108:109], v[110:111]
	v_pk_add_f32 v[98:99], v[112:113], v[114:115]
	v_mov_b32_e32 v108, v94
	v_mov_b32_e32 v109, v92
	v_mov_b32_e32 v92, v95
	v_mov_b32_e32 v94, v98
	v_mov_b32_e32 v95, v96
	v_mov_b32_e32 v96, v99
	v_pk_add_f32 v[92:93], v[108:109], v[92:93]
	v_pk_add_f32 v[94:95], v[94:95], v[96:97]
	ds_bpermute_b32 v97, v1, v93
	ds_bpermute_b32 v96, v1, v92
	v_pk_mul_f32 v[100:101], v[50:51], v[50:51]
	v_pk_mul_f32 v[102:103], v[46:47], v[46:47]
	v_pk_fma_f32 v[100:101], v[52:53], v[52:53], v[100:101]
	v_pk_fma_f32 v[102:103], v[48:49], v[48:49], v[102:103]
	s_waitcnt lgkmcnt(0)
	v_pk_add_f32 v[92:93], v[92:93], v[96:97]
	ds_bpermute_b32 v97, v86, v93
	ds_bpermute_b32 v96, v86, v92
	v_pk_add_f32 v[98:99], v[100:101], v[102:103]
	ds_bpermute_b32 v103, v1, v95
	ds_bpermute_b32 v102, v1, v94
	v_pk_mul_f32 v[104:105], v[20:21], v[20:21]
	s_waitcnt lgkmcnt(2)
	v_pk_add_f32 v[92:93], v[92:93], v[96:97]
	ds_bpermute_b32 v97, v87, v93
	ds_bpermute_b32 v96, v87, v92
	s_waitcnt lgkmcnt(2)
	v_pk_add_f32 v[94:95], v[94:95], v[102:103]
	ds_bpermute_b32 v103, v86, v95
	ds_bpermute_b32 v102, v86, v94
	v_pk_mul_f32 v[106:107], v[24:25], v[24:25]
	s_waitcnt lgkmcnt(2)
	v_pk_add_f32 v[92:93], v[92:93], v[96:97]
	ds_bpermute_b32 v97, v88, v93
	ds_bpermute_b32 v96, v88, v92
	s_waitcnt lgkmcnt(2)
	v_pk_add_f32 v[94:95], v[94:95], v[102:103]
	ds_bpermute_b32 v103, v87, v95
	ds_bpermute_b32 v102, v87, v94
	v_pk_fma_f32 v[104:105], v[18:19], v[18:19], v[104:105]
	s_waitcnt lgkmcnt(2)
	v_pk_add_f32 v[92:93], v[92:93], v[96:97]
	ds_bpermute_b32 v97, v89, v93
	ds_bpermute_b32 v96, v89, v92
	s_waitcnt lgkmcnt(2)
	v_pk_add_f32 v[94:95], v[94:95], v[102:103]
	ds_bpermute_b32 v103, v88, v95
	ds_bpermute_b32 v102, v88, v94
	v_pk_fma_f32 v[106:107], v[22:23], v[22:23], v[106:107]
	s_waitcnt lgkmcnt(2)
	v_pk_add_f32 v[92:93], v[92:93], v[96:97]
	ds_bpermute_b32 v97, v90, v93
	ds_bpermute_b32 v96, v90, v92
	s_waitcnt lgkmcnt(2)
	v_pk_add_f32 v[94:95], v[94:95], v[102:103]
	ds_bpermute_b32 v103, v89, v95
	ds_bpermute_b32 v102, v89, v94
	v_pk_add_f32 v[100:101], v[104:105], v[106:107]
	s_waitcnt lgkmcnt(2)
	v_pk_add_f32 v[92:93], v[92:93], v[96:97]
	v_mov_b32_e32 v104, v100
	v_pk_fma_f32 v[92:93], v[92:93], s[10:11], v[44:45] op_sel_hi:[1,0,0]
	s_waitcnt lgkmcnt(0)
; __device__ __forceinline__ unsigned cvt_pk_bf16(float lo, float hi) { unsigned r; asm volatile("v_cvt_pk_bf16_f32 %0, %1, %2" : "=v"(r) : "v"(lo), "v"(hi)); return r; }
; __device__ __forceinline__ float bflo(unsigned w) { return __uint_as_float(w << 16); }
; __device__ __forceinline__ float bfhi(unsigned w) { return __uint_as_float(w & 0xffff0000u); }
; __device__ __forceinline__ void gnorm_phase(bf16_t* YS, const float* ng, int gw, int NGW, int lane) {
;     ...
;             for (int g = 0; g < 8; ++g) sq[g] += __shfl_xor(sq[g], o);
; #pragma unroll
;         for (int g = 0; g < 8; ++g) { const float rstd = rsqrtf(sq[g] * (1.f / 512.f) + EPS);
;             const f32x4 g0 = *(const f32x4*)(ng + g * 512 + lane * 8), g1 = *(const f32x4*)(ng + g * 512 + lane * 8 + 4);
;             u32x4 o; o.x = cvt_pk_bf16(bflo(v[g].x) * rstd * g0[0], bfhi(v[g].x) * rstd * g0[1]); o.y = cvt_pk_bf16(bflo(v[g].y) * rstd * g0[2], bfhi(v[g].y) * rstd * g0[3]);
;             o.z = cvt_pk_bf16(bflo(v[g].z) * rstd * g1[0], bfhi(v[g].z) * rstd * g1[1]); o.w = cvt_pk_bf16(bflo(v[g].w) * rstd * g1[2], bfhi(v[g].w) * rstd * g1[3]);
;             *(u32x4*)(p + g * 512) = o; }
	v_pk_add_f32 v[94:95], v[94:95], v[102:103]
	v_mul_f32_e32 v91, 0x4b800000, v93
	v_cmp_gt_f32_e64 s[6:7], s86, v93
	v_mul_f32_e32 v96, 0x4b800000, v92
	v_cmp_gt_f32_e32 vcc, s86, v92
	v_cndmask_b32_e64 v91, v93, v91, s[6:7]
	v_rsq_f32_e32 v91, v91
	v_cndmask_b32_e32 v92, v92, v96, vcc
	v_rsq_f32_e32 v92, v92
	ds_bpermute_b32 v103, v90, v95
	v_mul_f32_e32 v93, 0x45800000, v91
	v_cndmask_b32_e64 v91, v91, v93, s[6:7]
	v_mul_f32_e32 v85, v91, v85
	v_mul_f32_e32 v78, v91, v78
	v_mul_f32_e32 v80, v91, v80
	v_mul_f32_e32 v82, v91, v82
	v_mul_f32_e32 v84, v91, v84
	v_mul_f32_e32 v79, v91, v79
	v_mul_f32_e32 v81, v91, v81
	v_mul_f32_e32 v83, v91, v83
	v_mul_f32_e32 v13, v13, v85
	v_mul_f32_e32 v14, v14, v78
	v_mul_f32_e32 v15, v15, v80
	v_mul_f32_e32 v16, v16, v82
	v_mul_f32_e32 v17, v17, v84
	v_mul_f32_e32 v78, v10, v79
	v_mul_f32_e32 v79, v11, v81
	v_mul_f32_e32 v80, v12, v83
	v_cvt_pk_bf16_f32 v10, v14, v15
	v_cvt_pk_bf16_f32 v11, v16, v17
	v_cvt_pk_bf16_f32 v12, v78, v79
	v_cvt_pk_bf16_f32 v13, v80, v13
	global_store_dwordx4 v[40:41], v[10:13], off
	s_nop 1
	v_mov_b64_e32 v[10:11], v[168:169]
	v_mov_b64_e32 v[12:13], v[170:171]
	s_nop 0
	s_nop 1
	v_mov_b64_e32 v[14:15], v[172:173]
	v_mov_b64_e32 v[16:17], v[174:175]
	v_mul_f32_e32 v96, 0x45800000, v92
	v_cndmask_b32_e32 v78, v92, v96, vcc
	v_mul_f32_e32 v70, v78, v70
	v_mul_f32_e32 v72, v78, v72
	v_mul_f32_e32 v74, v78, v74
	v_mul_f32_e32 v76, v78, v76
	v_mul_f32_e32 v71, v78, v71
	v_mul_f32_e32 v73, v78, v73
	v_mul_f32_e32 v75, v78, v75
	v_mul_f32_e32 v77, v78, v77
	ds_bpermute_b32 v102, v90, v94
	v_mov_b32_e32 v105, v98
	v_mov_b32_e32 v98, v101
	v_pk_add_f32 v[98:99], v[104:105], v[98:99]
	ds_bpermute_b32 v101, v1, v99
	ds_bpermute_b32 v100, v1, v98
	s_waitcnt lgkmcnt(0)
	v_pk_add_f32 v[98:99], v[98:99], v[100:101]
	ds_bpermute_b32 v101, v86, v99
	ds_bpermute_b32 v100, v86, v98
	v_mul_f32_e32 v10, v70, v10
	v_mul_f32_e32 v11, v72, v11
	v_mul_f32_e32 v12, v74, v12
	v_mul_f32_e32 v13, v76, v13
	v_mul_f32_e32 v14, v71, v14
	v_mul_f32_e32 v15, v73, v15
	v_mul_f32_e32 v16, v75, v16
	v_mul_f32_e32 v17, v77, v17
	v_cvt_pk_bf16_f32 v10, v10, v11
	v_cvt_pk_bf16_f32 v11, v12, v13
	v_cvt_pk_bf16_f32 v12, v14, v15
	v_cvt_pk_bf16_f32 v13, v16, v17
	global_store_dwordx4 v[40:41], v[10:13], off offset:1024
	s_nop 1
	v_mov_b64_e32 v[10:11], v[176:177]
	v_mov_b64_e32 v[12:13], v[178:179]
	s_nop 0
	s_nop 1
	v_mov_b64_e32 v[14:15], v[180:181]
	v_mov_b64_e32 v[16:17], v[182:183]
	v_pk_add_f32 v[70:71], v[94:95], v[102:103]
	s_nop 0
	v_pk_fma_f32 v[70:71], v[70:71], s[10:11], v[44:45] op_sel_hi:[1,0,0]
	s_nop 0
	v_mul_f32_e32 v72, 0x4b800000, v71
	v_cmp_gt_f32_e32 vcc, s86, v71
	s_nop 1
	v_cndmask_b32_e32 v71, v71, v72, vcc
	v_rsq_f32_e32 v71, v71
	s_nop 0
	v_mul_f32_e32 v72, 0x45800000, v71
	v_cndmask_b32_e32 v71, v71, v72, vcc
	v_mul_f32_e32 v62, v71, v62
	v_mul_f32_e32 v64, v71, v64
	v_mul_f32_e32 v66, v71, v66
	v_mul_f32_e32 v68, v71, v68
	v_mul_f32_e32 v63, v71, v63
	v_mul_f32_e32 v65, v71, v65
	v_mul_f32_e32 v67, v71, v67
	v_mul_f32_e32 v69, v71, v69
	v_cmp_gt_f32_e32 vcc, s86, v70
	v_mul_f32_e32 v10, v62, v10
	v_mul_f32_e32 v11, v64, v11
	v_mul_f32_e32 v12, v66, v12
	v_mul_f32_e32 v13, v68, v13
	v_mul_f32_e32 v14, v63, v14
	v_mul_f32_e32 v15, v65, v15
	v_mul_f32_e32 v16, v67, v16
	v_mul_f32_e32 v17, v69, v17
	v_cvt_pk_bf16_f32 v10, v10, v11
	v_cvt_pk_bf16_f32 v11, v12, v13
	v_cvt_pk_bf16_f32 v12, v14, v15
	v_cvt_pk_bf16_f32 v13, v16, v17
	global_store_dwordx4 v[40:41], v[10:13], off offset:2048
	s_nop 1
	v_mov_b64_e32 v[10:11], v[184:185]
	v_mov_b64_e32 v[12:13], v[186:187]
	s_nop 0
	s_nop 1
	v_mov_b64_e32 v[14:15], v[188:189]
	v_mov_b64_e32 v[16:17], v[190:191]
	s_waitcnt lgkmcnt(0)
	v_pk_add_f32 v[62:63], v[98:99], v[100:101]
	ds_bpermute_b32 v65, v87, v63
	ds_bpermute_b32 v64, v87, v62
	s_waitcnt lgkmcnt(0)
	v_pk_add_f32 v[62:63], v[62:63], v[64:65]
	v_mul_f32_e32 v64, 0x4b800000, v70
	v_cndmask_b32_e32 v64, v70, v64, vcc
	v_rsq_f32_e32 v64, v64
	s_nop 0
	v_mul_f32_e32 v65, 0x45800000, v64
	v_cndmask_b32_e32 v64, v64, v65, vcc
	v_mul_f32_e32 v54, v64, v54
	v_mul_f32_e32 v56, v64, v56
	v_mul_f32_e32 v58, v64, v58
	v_mul_f32_e32 v60, v64, v60
	v_mul_f32_e32 v55, v64, v55
	v_mul_f32_e32 v57, v64, v57
	v_mul_f32_e32 v59, v64, v59
	v_mul_f32_e32 v61, v64, v61
	v_mul_f32_e32 v10, v54, v10
	v_mul_f32_e32 v11, v56, v11
	v_mul_f32_e32 v12, v58, v12
	v_mul_f32_e32 v13, v60, v13
	v_mul_f32_e32 v14, v55, v14
	v_mul_f32_e32 v15, v57, v15
	v_mul_f32_e32 v16, v59, v16
	v_mul_f32_e32 v17, v61, v17
	v_cvt_pk_bf16_f32 v10, v10, v11
	v_cvt_pk_bf16_f32 v11, v12, v13
	v_cvt_pk_bf16_f32 v12, v14, v15
	v_cvt_pk_bf16_f32 v13, v16, v17
	global_store_dwordx4 v[40:41], v[10:13], off offset:3072
	s_nop 1
	v_mov_b64_e32 v[10:11], v[192:193]
	v_mov_b64_e32 v[12:13], v[194:195]
	s_nop 0
	s_nop 1
	v_mov_b64_e32 v[14:15], v[214:215]
	v_mov_b64_e32 v[16:17], v[216:217]
	ds_bpermute_b32 v55, v88, v63
	ds_bpermute_b32 v54, v88, v62
	v_and_b32_e32 v59, 0xffff0000, v4
	v_and_b32_e32 v58, 0xffff0000, v2
	v_lshlrev_b32_e32 v61, 16, v5
	v_lshlrev_b32_e32 v60, 16, v3
	s_waitcnt lgkmcnt(0)
	v_pk_add_f32 v[54:55], v[62:63], v[54:55]
	ds_bpermute_b32 v57, v89, v55
	ds_bpermute_b32 v56, v89, v54
	v_and_b32_e32 v63, 0xffff0000, v5
	v_and_b32_e32 v62, 0xffff0000, v3
	v_lshl_add_u64 v[40:41], v[40:41], 0, s[2:3]
	s_waitcnt lgkmcnt(0)
	v_pk_add_f32 v[54:55], v[54:55], v[56:57]
	ds_bpermute_b32 v57, v90, v55
	ds_bpermute_b32 v56, v90, v54
	s_waitcnt lgkmcnt(0)
; __device__ __forceinline__ unsigned cvt_pk_bf16(float lo, float hi) { unsigned r; asm volatile("v_cvt_pk_bf16_f32 %0, %1, %2" : "=v"(r) : "v"(lo), "v"(hi)); return r; }
; __device__ __forceinline__ float bflo(unsigned w) { return __uint_as_float(w << 16); }
; __device__ __forceinline__ float bfhi(unsigned w) { return __uint_as_float(w & 0xffff0000u); }
; __device__ __forceinline__ void gnorm_phase(bf16_t* YS, const float* ng, int gw, int NGW, int lane) {
;     ...
; #pragma unroll
;         for (int g = 0; g < 8; ++g) v[g] = *(const u32x4*)(p + g * 512);
; #pragma unroll
;         for (int g = 0; g < 8; ++g) { const float f0 = bflo(v[g].x), f1 = bfhi(v[g].x), f2 = bflo(v[g].y), f3 = bfhi(v[g].y), f4 = bflo(v[g].z), f5 = bfhi(v[g].z), f6 = bflo(v[g].w), f7 = bfhi(v[g].w);
;             sq[g] = ((f0 * f0 + f1 * f1) + (f2 * f2 + f3 * f3)) + ((f4 * f4 + f5 * f5) + (f6 * f6 + f7 * f7)); }
; #pragma unroll
;         for (int o = 1; o < 64; o <<= 1)
; #pragma unroll
;             for (int g = 0; g < 8; ++g) sq[g] += __shfl_xor(sq[g], o);
; #pragma unroll
;         for (int g = 0; g < 8; ++g) { const float rstd = rsqrtf(sq[g] * (1.f / 512.f) + EPS);
;             const f32x4 g0 = *(const f32x4*)(ng + g * 512 + lane * 8), g1 = *(const f32x4*)(ng + g * 512 + lane * 8 + 4);
;             u32x4 o; o.x = cvt_pk_bf16(bflo(v[g].x) * rstd * g0[0], bfhi(v[g].x) * rstd * g0[1]); o.y = cvt_pk_bf16(bflo(v[g].y) * rstd * g0[2], bfhi(v[g].y) * rstd * g0[3]);
;             o.z = cvt_pk_bf16(bflo(v[g].z) * rstd * g1[0], bfhi(v[g].z) * rstd * g1[1]); o.w = cvt_pk_bf16(bflo(v[g].w) * rstd * g1[2], bfhi(v[g].w) * rstd * g1[3]);
;             *(u32x4*)(p + g * 512) = o; }
	v_pk_add_f32 v[54:55], v[54:55], v[56:57]
	s_nop 0
	v_pk_fma_f32 v[54:55], v[54:55], s[10:11], v[44:45] op_sel_hi:[1,0,0]
	v_lshlrev_b32_e32 v57, 16, v4
	v_mul_f32_e32 v56, 0x4b800000, v55
	v_cmp_gt_f32_e32 vcc, s86, v55
	s_nop 1
	v_cndmask_b32_e32 v55, v55, v56, vcc
	v_rsq_f32_e32 v55, v55
	s_nop 0
	v_mul_f32_e32 v56, 0x45800000, v55
	v_cndmask_b32_e32 v55, v55, v56, vcc
	v_mul_f32_e32 v52, v55, v52
	v_mul_f32_e32 v50, v55, v50
	v_mul_f32_e32 v48, v55, v48
	v_mul_f32_e32 v46, v55, v46
	v_mul_f32_e32 v53, v55, v53
	v_mul_f32_e32 v51, v55, v51
	v_mul_f32_e32 v49, v55, v49
	v_mul_f32_e32 v47, v55, v47
	v_lshlrev_b32_e32 v56, 16, v2
	v_cmp_gt_f32_e32 vcc, s86, v54
	v_mul_f32_e32 v10, v52, v10
	v_mul_f32_e32 v11, v50, v11
	v_mul_f32_e32 v12, v48, v12
	v_mul_f32_e32 v13, v46, v13
	v_mul_f32_e32 v14, v53, v14
	v_mul_f32_e32 v15, v51, v15
	v_mul_f32_e32 v16, v49, v16
	v_mul_f32_e32 v17, v47, v17
	v_cvt_pk_bf16_f32 v10, v10, v11
	v_cvt_pk_bf16_f32 v11, v12, v13
	v_cvt_pk_bf16_f32 v12, v14, v15
	v_cvt_pk_bf16_f32 v13, v16, v17
	global_store_dwordx4 v[42:43], v[10:13], off
	s_nop 1
	v_mov_b64_e32 v[10:11], v[218:219]
	v_mov_b64_e32 v[12:13], v[220:221]
	s_nop 0
	s_nop 1
	v_mov_b64_e32 v[14:15], v[222:223]
	v_mov_b64_e32 v[16:17], v[224:225]
	v_and_b32_e32 v49, 0xffff0000, v8
	v_and_b32_e32 v48, 0xffff0000, v6
	v_and_b32_e32 v53, 0xffff0000, v9
	v_and_b32_e32 v52, 0xffff0000, v7
	v_lshlrev_b32_e32 v47, 16, v8
	v_lshlrev_b32_e32 v46, 16, v6
	v_lshlrev_b32_e32 v51, 16, v9
	v_lshlrev_b32_e32 v50, 16, v7
	v_pk_mul_f32 v[2:3], v[48:49], v[48:49]
	v_pk_mul_f32 v[4:5], v[52:53], v[52:53]
	v_pk_mul_f32 v[6:7], v[58:59], v[58:59]
	v_pk_mul_f32 v[8:9], v[62:63], v[62:63]
	v_pk_fma_f32 v[2:3], v[46:47], v[46:47], v[2:3]
	v_pk_fma_f32 v[4:5], v[50:51], v[50:51], v[4:5]
	v_pk_fma_f32 v[6:7], v[56:57], v[56:57], v[6:7]
	v_pk_fma_f32 v[8:9], v[60:61], v[60:61], v[8:9]
	v_pk_add_f32 v[2:3], v[2:3], v[4:5]
	v_pk_add_f32 v[4:5], v[6:7], v[8:9]
	v_mov_b32_e32 v7, v2
	v_mov_b32_e32 v6, v4
	v_mov_b32_e32 v2, v5
	v_pk_add_f32 v[64:65], v[6:7], v[2:3]
	v_mul_f32_e32 v2, 0x4b800000, v54
	v_cndmask_b32_e32 v2, v54, v2, vcc
	v_rsq_f32_e32 v2, v2
	ds_bpermute_b32 v55, v1, v65
	ds_bpermute_b32 v54, v1, v64
	v_mul_f32_e32 v3, 0x45800000, v2
	v_cndmask_b32_e32 v2, v2, v3, vcc
	v_mul_f32_e32 v3, v2, v18
	v_mul_f32_e32 v4, v2, v20
	v_mul_f32_e32 v5, v2, v22
	v_mul_f32_e32 v6, v2, v24
	v_mul_f32_e32 v7, v2, v19
	v_mul_f32_e32 v8, v2, v21
	v_mul_f32_e32 v9, v2, v23
	v_mul_f32_e32 v2, v2, v25
	v_mul_f32_e32 v3, v3, v10
	v_mul_f32_e32 v4, v4, v11
	v_mul_f32_e32 v5, v5, v12
	v_mul_f32_e32 v6, v6, v13
	v_mul_f32_e32 v7, v7, v14
	v_mul_f32_e32 v8, v8, v15
	v_mul_f32_e32 v9, v9, v16
	v_mul_f32_e32 v10, v2, v17
	v_cvt_pk_bf16_f32 v2, v3, v4
	v_cvt_pk_bf16_f32 v3, v5, v6
	v_cvt_pk_bf16_f32 v4, v7, v8
	v_cvt_pk_bf16_f32 v5, v9, v10
	global_store_dwordx4 v[42:43], v[2:5], off offset:1024
	s_nop 1
	v_mov_b64_e32 v[2:3], v[226:227]
	v_mov_b64_e32 v[4:5], v[228:229]
	s_nop 0
	s_nop 1
	v_mov_b64_e32 v[6:7], v[230:231]
	v_mov_b64_e32 v[8:9], v[232:233]
	s_waitcnt lgkmcnt(0)
	v_pk_add_f32 v[10:11], v[64:65], v[54:55]
	ds_bpermute_b32 v13, v86, v11
	ds_bpermute_b32 v12, v86, v10
	s_waitcnt lgkmcnt(0)
	v_pk_add_f32 v[10:11], v[10:11], v[12:13]
	ds_bpermute_b32 v13, v87, v11
	ds_bpermute_b32 v12, v87, v10
	s_waitcnt lgkmcnt(0)
	v_pk_add_f32 v[10:11], v[10:11], v[12:13]
	ds_bpermute_b32 v13, v88, v11
	ds_bpermute_b32 v12, v88, v10
	s_waitcnt lgkmcnt(0)
	v_pk_add_f32 v[10:11], v[10:11], v[12:13]
	ds_bpermute_b32 v13, v89, v11
	ds_bpermute_b32 v12, v89, v10
	s_waitcnt lgkmcnt(0)
	v_pk_add_f32 v[10:11], v[10:11], v[12:13]
	ds_bpermute_b32 v13, v90, v11
	ds_bpermute_b32 v12, v90, v10
	s_waitcnt lgkmcnt(0)
	v_pk_add_f32 v[10:11], v[10:11], v[12:13]
	s_nop 0
	v_pk_fma_f32 v[10:11], v[10:11], s[10:11], v[44:45] op_sel_hi:[1,0,0]
	s_nop 0
	v_mul_f32_e32 v12, 0x4b800000, v11
	v_cmp_gt_f32_e32 vcc, s86, v11
	s_nop 1
	v_cndmask_b32_e32 v11, v11, v12, vcc
	v_rsq_f32_e32 v11, v11
	s_nop 0
	v_mul_f32_e32 v12, 0x45800000, v11
	v_cndmask_b32_e32 v11, v11, v12, vcc
	v_mul_f32_e32 v12, v11, v46
	v_mul_f32_e32 v13, v11, v48
	v_mul_f32_e32 v14, v11, v50
	v_mul_f32_e32 v15, v11, v52
	v_mul_f32_e32 v16, v11, v47
	v_mul_f32_e32 v17, v11, v49
	v_mul_f32_e32 v18, v11, v51
	v_mul_f32_e32 v11, v11, v53
	v_cmp_gt_f32_e32 vcc, s86, v10
	v_mul_f32_e32 v2, v12, v2
	v_mul_f32_e32 v3, v13, v3
	v_mul_f32_e32 v4, v14, v4
	v_mul_f32_e32 v5, v15, v5
	v_mul_f32_e32 v6, v16, v6
	v_mul_f32_e32 v7, v17, v7
	v_mul_f32_e32 v8, v18, v8
	v_mul_f32_e32 v9, v11, v9
	v_cvt_pk_bf16_f32 v2, v2, v3
	v_cvt_pk_bf16_f32 v3, v4, v5
	v_cvt_pk_bf16_f32 v4, v6, v7
	v_cvt_pk_bf16_f32 v5, v8, v9
	global_store_dwordx4 v[42:43], v[2:5], off offset:2048
	s_nop 1
	v_mov_b64_e32 v[2:3], v[234:235]
	v_mov_b64_e32 v[4:5], v[236:237]
	s_nop 0
	s_nop 1
	v_mov_b64_e32 v[6:7], v[238:239]
	v_mov_b64_e32 v[8:9], v[240:241]
	v_mul_f32_e32 v11, 0x4b800000, v10
	v_cndmask_b32_e32 v10, v10, v11, vcc
	v_rsq_f32_e32 v10, v10
	s_nop 0
	v_mul_f32_e32 v11, 0x45800000, v10
	v_cndmask_b32_e32 v10, v10, v11, vcc
	v_mul_f32_e32 v11, v10, v56
	v_mul_f32_e32 v12, v10, v58
	v_mul_f32_e32 v13, v10, v60
	v_mul_f32_e32 v14, v10, v62
	v_mul_f32_e32 v15, v10, v57
	v_mul_f32_e32 v16, v10, v59
	v_mul_f32_e32 v17, v10, v61
	v_mul_f32_e32 v10, v10, v63
	v_mul_f32_e32 v2, v11, v2
	v_mul_f32_e32 v3, v12, v3
	v_mul_f32_e32 v4, v13, v4
	v_mul_f32_e32 v5, v14, v5
	v_mul_f32_e32 v6, v15, v6
	v_mul_f32_e32 v7, v16, v7
	v_mul_f32_e32 v8, v17, v8
	v_mul_f32_e32 v9, v10, v9
	v_cvt_pk_bf16_f32 v2, v2, v3
	v_cvt_pk_bf16_f32 v3, v4, v5
	v_cvt_pk_bf16_f32 v4, v6, v7
	v_cvt_pk_bf16_f32 v5, v8, v9
	global_store_dwordx4 v[42:43], v[2:5], off offset:3072
	s_cbranch_scc0 .LBB0_88

; __device__ __forceinline__ unsigned cvt_pk_bf16(float lo, float hi) { unsigned r; asm volatile("v_cvt_pk_bf16_f32 %0, %1, %2" : "=v"(r) : "v"(lo), "v"(hi)); return r; }
; __device__ __forceinline__ void rms_row(const float* xrow, const float* g, bf16_t* orow, int lane) {
;     const f32x4* xr = (const f32x4*)xrow + lane; f32x4 v[8]; float s = 0.f;
; #pragma unroll
;     for (int j = 0; j < 8; ++j) { v[j] = xr[64 * j]; s += (v[j][0] * v[j][0] + v[j][1] * v[j][1]) + (v[j][2] * v[j][2] + v[j][3] * v[j][3]); }
;     const float rstd = rsqrtf(wave_sum(s) * (1.f / D) + EPS);
;     const f32x4* gr = (const f32x4*)g + lane;
; #pragma unroll
;     for (int j = 0; j < 8; ++j) { const f32x4 gv = gr[64 * j]; const f32x4 o = v[j] * rstd * gv; u32x2 w; w.x = cvt_pk_bf16(o[0], o[1]); w.y = cvt_pk_bf16(o[2], o[3]); ((u32x2*)orow)[lane + 64 * j] = w; }
; }
; __device__ __forceinline__ void rms_phase(const float* X, const float* g, bf16_t* O, int gw, int NGW, int lane) {
;     for (int m = gw; m < T; m += NGW) rms_row(X + (size_t)m * D, g, O + (size_t)m * D, lane);
.LBB0_693:
	s_andn2_b64 vcc, exec, s[6:7]
	s_cbranch_vccnz .LBB0_701
	v_readlane_b32 s0, v254, 39
	s_cmpk_gt_i32 s0, 0x1fff
	v_readlane_b32 s8, v254, 41
	v_readlane_b32 s1, v254, 40
	v_readlane_b32 s9, v254, 42
	s_cbranch_scc1 .LBB0_697
	v_xor_b32_e32 v1, 1, v200
	v_cmp_lt_i32_e32 vcc, v1, v202
	v_xor_b32_e32 v2, 2, v200
	v_readlane_b32 s12, v254, 45
	v_cndmask_b32_e32 v1, v200, v1, vcc
	v_cmp_lt_i32_e32 vcc, v2, v202
	v_mov_b32_e32 v3, v0
	v_readlane_b32 s16, v254, 49
	v_cndmask_b32_e32 v2, v200, v2, vcc
	v_lshlrev_b32_e32 v53, 2, v2
	v_xor_b32_e32 v2, 4, v200
	v_cmp_lt_i32_e32 vcc, v2, v202
	v_readlane_b32 s17, v254, 50
	v_readlane_b32 s6, v254, 39
	v_cndmask_b32_e32 v2, v200, v2, vcc
	v_cmp_lt_i32_e32 vcc, v206, v202
	v_lshlrev_b32_e32 v54, 2, v2
	s_mov_b64 s[0:1], 0x1400
	v_cndmask_b32_e32 v2, v200, v206, vcc
	v_cmp_lt_i32_e32 vcc, v207, v202
	v_lshlrev_b32_e32 v55, 2, v2
	v_readlane_b32 s7, v254, 40
	v_cndmask_b32_e32 v2, v200, v207, vcc
	v_cmp_lt_i32_e32 vcc, v208, v202
	v_lshlrev_b32_e32 v56, 2, v2
	s_ashr_i32 s7, s6, 31
	v_cndmask_b32_e32 v2, v200, v208, vcc
	v_lshlrev_b32_e32 v57, 2, v2
	v_lshlrev_b32_e32 v2, 4, v211
	v_lshl_add_u64 v[38:39], s[16:17], 0, v[2:3]
	v_lshl_add_u64 v[42:43], v[38:39], 0, s[0:1]
	s_mov_b64 s[0:1], 0x1800
	v_lshl_add_u64 v[44:45], v[38:39], 0, s[0:1]
	s_mov_b64 s[0:1], 0x1c00
	v_lshl_add_u64 v[46:47], v[38:39], 0, s[0:1]
	s_lshl_b64 s[0:1], s[6:7], 13
	v_readlane_b32 s13, v254, 46
	s_add_u32 s0, s12, s0
	s_addc_u32 s1, s13, s1
	s_mov_b64 s[2:3], 0x1000
	v_lshl_add_u64 v[2:3], s[0:1], 0, v[2:3]
	s_ashr_i32 s9, s8, 31
	v_lshl_add_u64 v[40:41], v[38:39], 0, s[2:3]
	v_lshl_add_u64 v[48:49], v[2:3], 0, s[2:3]
	s_lshl_b64 s[0:1], s[8:9], 13
	s_lshl_b64 s[2:3], s[6:7], 12
	s_add_u32 s2, s96, s2
	v_lshlrev_b32_e32 v2, 3, v211
	v_mov_b32_e32 v3, v0
	s_addc_u32 s3, s97, s3
	v_lshlrev_b32_e32 v1, 2, v1
	v_lshl_add_u64 v[50:51], s[2:3], 0, v[2:3]
	s_lshl_b64 s[2:3], s[8:9], 12
	v_readlane_b32 s14, v254, 47
	v_readlane_b32 s15, v254, 48
	v_readlane_b32 s18, v254, 51
	v_readlane_b32 s19, v254, 52
	global_load_dwordx4 v[62:65], v[48:49], off offset:-4096
	global_load_dwordx4 v[66:69], v[48:49], off offset:-3072
	global_load_dwordx4 v[70:73], v[48:49], off offset:-2048
	global_load_dwordx4 v[74:77], v[48:49], off offset:-1024
	global_load_dwordx4 v[78:81], v[48:49], off
	global_load_dwordx4 v[82:85], v[48:49], off offset:1024
	global_load_dwordx4 v[86:89], v[48:49], off offset:2048
	global_load_dwordx4 v[90:93], v[48:49], off offset:3072
	global_load_dwordx4 v[94:97], v[38:39], off
	global_load_dwordx4 v[98:101], v[38:39], off offset:1024
	global_load_dwordx4 v[102:105], v[38:39], off offset:2048
	global_load_dwordx4 v[106:109], v[38:39], off offset:3072
	global_load_dwordx4 v[110:113], v[40:41], off
	global_load_dwordx4 v[114:117], v[42:43], off
	global_load_dwordx4 v[118:121], v[44:45], off
	global_load_dwordx4 v[122:125], v[46:47], off
	s_waitcnt vmcnt(0)
.LBB0_696:
	s_add_i32 s6, s6, s8
	s_cmpk_lt_i32 s6, 0x2000
	s_cbranch_scc0 .Lrms_last0
	s_waitcnt vmcnt(14)
	v_mov_b64_e32 v[6:7], v[62:63]
	v_mov_b64_e32 v[8:9], v[64:65]
	v_mov_b64_e32 v[2:3], v[66:67]
	v_mov_b64_e32 v[4:5], v[68:69]
	v_lshl_add_u64 v[126:127], v[48:49], 0, s[0:1]
	global_load_dwordx4 v[62:65], v[126:127], off offset:-4096
	global_load_dwordx4 v[66:69], v[126:127], off offset:-3072
	s_branch .Lrms_join0
.Lrms_last0:
	s_waitcnt vmcnt(14)
	v_mov_b64_e32 v[6:7], v[62:63]
	v_mov_b64_e32 v[8:9], v[64:65]
	v_mov_b64_e32 v[2:3], v[66:67]
	v_mov_b64_e32 v[4:5], v[68:69]
.Lrms_join0:
	v_mov_b32_e32 v12, v7
	v_mov_b32_e32 v13, v3
	v_mov_b32_e32 v10, v6
	v_mov_b32_e32 v11, v2
	v_pk_mul_f32 v[12:13], v[12:13], v[12:13]
	v_mov_b32_e32 v14, v9
	v_mov_b32_e32 v15, v5
	v_pk_fma_f32 v[10:11], v[10:11], v[10:11], v[12:13]
	v_mov_b32_e32 v12, v8
	v_mov_b32_e32 v13, v4
	v_pk_mul_f32 v[14:15], v[14:15], v[14:15]
	s_nop 0
	v_pk_fma_f32 v[12:13], v[12:13], v[12:13], v[14:15]
	v_pk_add_f32 v[22:23], v[10:11], v[12:13]
	s_cbranch_scc0 .Lrms_last1
	s_waitcnt vmcnt(15)
	v_mov_b64_e32 v[14:15], v[70:71]
	v_mov_b64_e32 v[16:17], v[72:73]
	global_load_dwordx4 v[70:73], v[126:127], off offset:-2048
	s_branch .Lrms_join1
.Lrms_last1:
	s_waitcnt vmcnt(13)
	v_mov_b64_e32 v[14:15], v[70:71]
	v_mov_b64_e32 v[16:17], v[72:73]
.Lrms_join1:
	v_pk_mul_f32 v[10:11], v[16:17], v[16:17]
	v_pk_mul_f32 v[12:13], v[14:15], v[14:15]
	v_pk_add_f32 v[22:23], v[22:23], v[22:23] op_sel:[0,1] op_sel_hi:[1,0]
	v_pk_mov_b32 v[18:19], v[12:13], v[10:11] op_sel:[1,0]
	v_mov_b32_e32 v13, v11
	v_pk_add_f32 v[24:25], v[18:19], v[12:13]
	v_pk_add_f32 v[24:25], v[24:25], v[24:25] op_sel:[0,1] op_sel_hi:[1,0]
	s_cbranch_scc0 .Lrms_last2
	s_waitcnt vmcnt(14)
	v_mov_b64_e32 v[10:11], v[74:75]
	v_mov_b64_e32 v[12:13], v[76:77]
	v_mov_b64_e32 v[18:19], v[78:79]
	v_mov_b64_e32 v[20:21], v[80:81]
	global_load_dwordx4 v[74:77], v[126:127], off offset:-1024
	global_load_dwordx4 v[78:81], v[126:127], off
	s_branch .Lrms_join2
.Lrms_last2:
	s_waitcnt vmcnt(11)
	v_mov_b64_e32 v[10:11], v[74:75]
	v_mov_b64_e32 v[12:13], v[76:77]
	v_mov_b64_e32 v[18:19], v[78:79]
	v_mov_b64_e32 v[20:21], v[80:81]
.Lrms_join2:
	v_mul_f32_e32 v26, v18, v18
	v_mul_f32_e32 v27, v19, v19
	v_mov_b32_e32 v23, v26
	v_mov_b32_e32 v25, v27
	v_pk_add_f32 v[22:23], v[22:23], v[24:25]
	v_mul_f32_e32 v24, v11, v11
	v_mul_f32_e32 v26, v13, v13
	v_mul_f32_e32 v28, v20, v20
	v_mul_f32_e32 v29, v21, v21
	v_pk_fma_f32 v[24:25], v[10:11], v[10:11], v[24:25] op_sel_hi:[1,1,0]
	v_pk_fma_f32 v[26:27], v[12:13], v[12:13], v[26:27] op_sel_hi:[1,1,0]
	v_mov_b32_e32 v25, v28
	v_mov_b32_e32 v27, v29
	v_pk_add_f32 v[24:25], v[24:25], v[26:27]
	s_nop 0
	v_pk_add_f32 v[34:35], v[22:23], v[24:25]
	v_pk_add_f32 v[34:35], v[34:35], v[34:35] op_sel:[0,1] op_sel_hi:[1,0]
	s_cbranch_scc0 .Lrms_last3
	s_waitcnt vmcnt(15)
	v_mov_b64_e32 v[22:23], v[82:83]
	v_mov_b64_e32 v[24:25], v[84:85]
	global_load_dwordx4 v[82:85], v[126:127], off offset:1024
	s_branch .Lrms_join3
; __device__ __forceinline__ unsigned cvt_pk_bf16(float lo, float hi) { unsigned r; asm volatile("v_cvt_pk_bf16_f32 %0, %1, %2" : "=v"(r) : "v"(lo), "v"(hi)); return r; }
; __device__ __forceinline__ void rms_row(const float* xrow, const float* g, bf16_t* orow, int lane) {
;     const f32x4* xr = (const f32x4*)xrow + lane; f32x4 v[8]; float s = 0.f;
; #pragma unroll
;     for (int j = 0; j < 8; ++j) { v[j] = xr[64 * j]; s += (v[j][0] * v[j][0] + v[j][1] * v[j][1]) + (v[j][2] * v[j][2] + v[j][3] * v[j][3]); }
;     const float rstd = rsqrtf(wave_sum(s) * (1.f / D) + EPS);
;     const f32x4* gr = (const f32x4*)g + lane;
; #pragma unroll
;     for (int j = 0; j < 8; ++j) { const f32x4 gv = gr[64 * j]; const f32x4 o = v[j] * rstd * gv; u32x2 w; w.x = cvt_pk_bf16(o[0], o[1]); w.y = cvt_pk_bf16(o[2], o[3]); ((u32x2*)orow)[lane + 64 * j] = w; }
; }
.Lrms_last3:
	s_waitcnt vmcnt(10)
	v_mov_b64_e32 v[22:23], v[82:83]
	v_mov_b64_e32 v[24:25], v[84:85]
.Lrms_join3:
	v_pk_mul_f32 v[26:27], v[24:25], v[24:25]
	v_pk_mul_f32 v[28:29], v[22:23], v[22:23]
	s_nop 0
	v_pk_mov_b32 v[30:31], v[28:29], v[26:27] op_sel:[1,0]
	v_mov_b32_e32 v29, v27
	v_pk_add_f32 v[36:37], v[30:31], v[28:29]
	v_pk_add_f32 v[36:37], v[36:37], v[36:37] op_sel:[0,1] op_sel_hi:[1,0]
	v_lshl_add_u64 v[48:49], v[48:49], 0, s[0:1]
	s_cbranch_scc0 .Lrms_last4
	s_waitcnt vmcnt(14)
	v_mov_b64_e32 v[30:31], v[86:87]
	v_mov_b64_e32 v[32:33], v[88:89]
	v_mov_b64_e32 v[26:27], v[90:91]
	v_mov_b64_e32 v[28:29], v[92:93]
	global_load_dwordx4 v[86:89], v[126:127], off offset:2048
	global_load_dwordx4 v[90:93], v[126:127], off offset:3072
	s_branch .Lrms_join4
.Lrms_last4:
	s_waitcnt vmcnt(8)
	v_mov_b64_e32 v[30:31], v[86:87]
	v_mov_b64_e32 v[32:33], v[88:89]
	v_mov_b64_e32 v[26:27], v[90:91]
	v_mov_b64_e32 v[28:29], v[92:93]
.Lrms_join4:
	v_mul_f32_e32 v52, v26, v26
	v_mul_f32_e32 v58, v27, v27
	v_mov_b32_e32 v35, v52
	v_mov_b32_e32 v37, v58
	v_pk_add_f32 v[34:35], v[34:35], v[36:37]
	v_mul_f32_e32 v36, v31, v31
	v_mul_f32_e32 v59, v28, v28
	v_pk_fma_f32 v[36:37], v[30:31], v[30:31], v[36:37] op_sel_hi:[1,1,0]
	v_mul_f32_e32 v52, v33, v33
	v_mul_f32_e32 v60, v29, v29
	v_mov_b32_e32 v37, v59
	v_pk_fma_f32 v[58:59], v[32:33], v[32:33], v[52:53] op_sel_hi:[1,1,0]
	s_nop 0
	v_mov_b32_e32 v59, v60
	v_pk_add_f32 v[36:37], v[36:37], v[58:59]
	s_nop 0
	v_pk_add_f32 v[34:35], v[34:35], v[36:37]
	s_nop 0
	v_add_f32_e32 v34, v34, v35
	ds_bpermute_b32 v35, v1, v34
	s_waitcnt lgkmcnt(0)
	v_add_f32_e32 v34, v34, v35
	ds_bpermute_b32 v35, v53, v34
	s_waitcnt lgkmcnt(0)
	v_add_f32_e32 v34, v34, v35
	ds_bpermute_b32 v35, v54, v34
	s_waitcnt lgkmcnt(0)
	v_add_f32_e32 v34, v34, v35
	ds_bpermute_b32 v35, v55, v34
	s_waitcnt lgkmcnt(0)
	v_add_f32_e32 v34, v34, v35
	ds_bpermute_b32 v35, v56, v34
	s_waitcnt lgkmcnt(0)
	v_add_f32_e32 v34, v34, v35
	ds_bpermute_b32 v35, v57, v34
	s_waitcnt lgkmcnt(0)
	v_add_f32_e32 v34, v34, v35
	v_fmamk_f32 v34, v34, 0x3a000000, v142
	v_cmp_gt_f32_e32 vcc, s86, v34
	v_mul_f32_e32 v35, 0x4b800000, v34
	s_nop 0
	v_cndmask_b32_e32 v34, v34, v35, vcc
	v_rsq_f32_e32 v34, v34
	s_nop 0
	v_mul_f32_e32 v35, 0x45800000, v34
	v_cndmask_b32_e32 v52, v34, v35, vcc
	v_pk_mul_f32 v[6:7], v[6:7], v[52:53] op_sel_hi:[1,0]
	v_pk_mul_f32 v[8:9], v[8:9], v[52:53] op_sel_hi:[1,0]
	v_pk_mul_f32 v[2:3], v[2:3], v[52:53] op_sel_hi:[1,0]
	v_pk_mul_f32 v[4:5], v[4:5], v[52:53] op_sel_hi:[1,0]
	v_mov_b64_e32 v[34:35], v[94:95]
	v_mov_b64_e32 v[36:37], v[96:97]
	v_pk_mul_f32 v[6:7], v[34:35], v[6:7]
	v_pk_mul_f32 v[8:9], v[36:37], v[8:9]
	v_cvt_pk_bf16_f32 v6, v6, v7
	s_nop 0
	v_cvt_pk_bf16_f32 v7, v8, v9
	global_store_dwordx2 v[50:51], v[6:7], off
	v_mov_b64_e32 v[6:7], v[98:99]
	v_mov_b64_e32 v[8:9], v[100:101]
	v_pk_mul_f32 v[2:3], v[6:7], v[2:3]
	v_pk_mul_f32 v[4:5], v[8:9], v[4:5]
	v_cvt_pk_bf16_f32 v2, v2, v3
	v_pk_mul_f32 v[6:7], v[14:15], v[52:53] op_sel_hi:[1,0]
	v_cvt_pk_bf16_f32 v3, v4, v5
	global_store_dwordx2 v[50:51], v[2:3], off offset:512
	v_pk_mul_f32 v[8:9], v[16:17], v[52:53] op_sel_hi:[1,0]
	v_mov_b64_e32 v[2:3], v[102:103]
	v_mov_b64_e32 v[4:5], v[104:105]
	v_pk_mul_f32 v[2:3], v[2:3], v[6:7]
	v_pk_mul_f32 v[4:5], v[4:5], v[8:9]
	v_cvt_pk_bf16_f32 v2, v2, v3
	v_pk_mul_f32 v[6:7], v[10:11], v[52:53] op_sel_hi:[1,0]
	v_cvt_pk_bf16_f32 v3, v4, v5
	global_store_dwordx2 v[50:51], v[2:3], off offset:1024
	v_pk_mul_f32 v[8:9], v[12:13], v[52:53] op_sel_hi:[1,0]
	v_mov_b64_e32 v[2:3], v[106:107]
	v_mov_b64_e32 v[4:5], v[108:109]
	v_pk_mul_f32 v[2:3], v[2:3], v[6:7]
	v_pk_mul_f32 v[4:5], v[4:5], v[8:9]
	v_cvt_pk_bf16_f32 v2, v2, v3
	v_pk_mul_f32 v[6:7], v[18:19], v[52:53] op_sel_hi:[1,0]
	v_cvt_pk_bf16_f32 v3, v4, v5
	global_store_dwordx2 v[50:51], v[2:3], off offset:1536
	v_pk_mul_f32 v[8:9], v[20:21], v[52:53] op_sel_hi:[1,0]
	v_mov_b64_e32 v[2:3], v[110:111]
	v_mov_b64_e32 v[4:5], v[112:113]
	v_pk_mul_f32 v[2:3], v[6:7], v[2:3]
	v_pk_mul_f32 v[4:5], v[8:9], v[4:5]
	v_cvt_pk_bf16_f32 v2, v2, v3
	v_pk_mul_f32 v[6:7], v[22:23], v[52:53] op_sel_hi:[1,0]
	v_cvt_pk_bf16_f32 v3, v4, v5
	global_store_dwordx2 v[50:51], v[2:3], off offset:2048
	v_pk_mul_f32 v[8:9], v[24:25], v[52:53] op_sel_hi:[1,0]
	v_mov_b64_e32 v[2:3], v[114:115]
	v_mov_b64_e32 v[4:5], v[116:117]
	v_pk_mul_f32 v[2:3], v[6:7], v[2:3]
	v_pk_mul_f32 v[4:5], v[8:9], v[4:5]
	v_cvt_pk_bf16_f32 v2, v2, v3
	v_pk_mul_f32 v[6:7], v[30:31], v[52:53] op_sel_hi:[1,0]
	v_cvt_pk_bf16_f32 v3, v4, v5
	global_store_dwordx2 v[50:51], v[2:3], off offset:2560
	v_pk_mul_f32 v[8:9], v[32:33], v[52:53] op_sel_hi:[1,0]
	v_mov_b64_e32 v[2:3], v[118:119]
	v_mov_b64_e32 v[4:5], v[120:121]
	v_pk_mul_f32 v[2:3], v[6:7], v[2:3]
	v_pk_mul_f32 v[4:5], v[8:9], v[4:5]
	v_cvt_pk_bf16_f32 v2, v2, v3
	v_pk_mul_f32 v[6:7], v[26:27], v[52:53] op_sel_hi:[1,0]
	v_cvt_pk_bf16_f32 v3, v4, v5
	global_store_dwordx2 v[50:51], v[2:3], off offset:3072
	v_pk_mul_f32 v[8:9], v[28:29], v[52:53] op_sel_hi:[1,0]
	v_mov_b64_e32 v[2:3], v[122:123]
	v_mov_b64_e32 v[4:5], v[124:125]
	v_pk_mul_f32 v[2:3], v[6:7], v[2:3]
	v_pk_mul_f32 v[4:5], v[8:9], v[4:5]
	v_cvt_pk_bf16_f32 v2, v2, v3
	s_nop 0
	v_cvt_pk_bf16_f32 v3, v4, v5
	global_store_dwordx2 v[50:51], v[2:3], off offset:3584
	v_lshl_add_u64 v[50:51], v[50:51], 0, s[2:3]
	s_cbranch_scc1 .LBB0_696
